# v21
# speedup vs baseline: 1.0014x; 1.0014x over previous
.LBB0_958:
	ds_read_b128 v[64:67], v195 offset:49152
	ds_read_b128 v[68:71], v195 offset:57344
	ds_read_b128 v[232:235], v226 offset:49152
	ds_read_b128 v[236:239], v226 offset:57344
	v_add_f32_e32 v160, 0, v161
	v_add_f32_e32 v160, v175, v160
	s_waitcnt lgkmcnt(3)
	v_mfma_f32_32x32x16_bf16 v[80:95], v[64:67], v[112:115], 0
	v_add_f32_e32 v160, v162, v160
	v_add_f32_e32 v160, v186, v160
	v_add_f32_e32 v160, v174, v160
	v_add_f32_e32 v160, v187, v160
	v_add_f32_e32 v160, v163, v160
	v_add_f32_e32 v160, v173, v160
	v_add_f32_e32 v160, v164, v160
	s_waitcnt lgkmcnt(2)
	v_mfma_f32_32x32x16_bf16 v[64:79], v[68:71], v[112:115], 0
	v_add_f32_e32 v160, v171, v160
	v_add_f32_e32 v160, v165, v160
	v_add_f32_e32 v160, v172, v160
	v_exp_f32_e32 v158, v158
	v_add_f32_e32 v160, v166, v160
	v_exp_f32_e32 v159, v159
	v_add_f32_e32 v160, v169, v160
	s_waitcnt lgkmcnt(1)
	v_mfma_f32_32x32x16_bf16 v[80:95], v[232:235], v[108:111], v[80:95]
	v_exp_f32_e32 v156, v156
	v_add_f32_e32 v160, v167, v160
	v_exp_f32_e32 v157, v157
	v_add_f32_e32 v160, v170, v160
	v_exp_f32_e32 v152, v152
	v_add_f32_e32 v160, v158, v160
	v_exp_f32_e32 v153, v153
	s_waitcnt lgkmcnt(0)
	v_mfma_f32_32x32x16_bf16 v[64:79], v[236:239], v[108:111], v[64:79]
	ds_read_b128 v[232:235], v225 offset:49152
	ds_read_b128 v[236:239], v225 offset:57344
	v_add_f32_e32 v160, v159, v160
	v_exp_f32_e32 v148, v148
	v_add_f32_e32 v160, v156, v160
	v_exp_f32_e32 v149, v149
	v_add_f32_e32 v160, v157, v160
	v_exp_f32_e32 v144, v144
	s_waitcnt lgkmcnt(1)
	v_mfma_f32_32x32x16_bf16 v[80:95], v[232:235], v[120:123], v[80:95]
	v_add_f32_e32 v160, v152, v160
	v_exp_f32_e32 v145, v145
	v_add_f32_e32 v160, v153, v160
	v_exp_f32_e32 v154, v154
	v_add_f32_e32 v160, v148, v160
	v_exp_f32_e32 v155, v155
	v_add_f32_e32 v160, v149, v160
	s_waitcnt lgkmcnt(0)
	v_mfma_f32_32x32x16_bf16 v[64:79], v[236:239], v[120:123], v[64:79]
	ds_read_b128 v[232:235], v224 offset:49152
	ds_read_b128 v[236:239], v224 offset:57344
	v_exp_f32_e32 v150, v150
	v_add_f32_e32 v160, v144, v160
	v_exp_f32_e32 v151, v151
	v_add_f32_e32 v160, v145, v160
	v_exp_f32_e32 v146, v146
	v_add_f32_e32 v160, v154, v160
	s_waitcnt lgkmcnt(1)
	v_mfma_f32_32x32x16_bf16 v[80:95], v[232:235], v[124:127], v[80:95]
	v_exp_f32_e32 v147, v147
	v_add_f32_e32 v160, v155, v160
	v_add_f32_e32 v160, v150, v160
	v_add_f32_e32 v160, v151, v160
	v_add_f32_e32 v160, v146, v160
	v_add_f32_e32 v231, v147, v160
	s_waitcnt lgkmcnt(0)
	v_mfma_f32_32x32x16_bf16 v[64:79], v[236:239], v[124:127], v[64:79]
	ds_read_b128 v[232:235], v223 offset:49152
	ds_read_b128 v[236:239], v223 offset:57344
	s_waitcnt lgkmcnt(1)
	v_mfma_f32_32x32x16_bf16 v[80:95], v[232:235], v[116:119], v[80:95]
	s_waitcnt lgkmcnt(0)
	v_mfma_f32_32x32x16_bf16 v[64:79], v[236:239], v[116:119], v[64:79]
	ds_read_b128 v[232:235], v227 offset:49152
	ds_read_b128 v[236:239], v227 offset:57344
	s_waitcnt lgkmcnt(1)
	v_mfma_f32_32x32x16_bf16 v[80:95], v[232:235], v[104:107], v[80:95]
	s_waitcnt lgkmcnt(0)
	v_mfma_f32_32x32x16_bf16 v[64:79], v[236:239], v[104:107], v[64:79]
	ds_read_b128 v[232:235], v228 offset:49152
	ds_read_b128 v[236:239], v228 offset:57344
	s_waitcnt lgkmcnt(1)
	v_mfma_f32_32x32x16_bf16 v[80:95], v[232:235], v[100:103], v[80:95]
	s_waitcnt lgkmcnt(0)
	v_mfma_f32_32x32x16_bf16 v[64:79], v[236:239], v[100:103], v[64:79]
	ds_read_b128 v[232:235], v229 offset:49152
	ds_read_b128 v[236:239], v229 offset:57344
	v_cvt_pk_bf16_f32 v160, v161, v175
	v_cvt_pk_bf16_f32 v161, v162, v186
	v_cvt_pk_bf16_f32 v162, v174, v187
	v_cvt_pk_bf16_f32 v163, v163, v173
	v_cvt_pk_bf16_f32 v164, v164, v171
	v_cvt_pk_bf16_f32 v165, v165, v172
	s_waitcnt lgkmcnt(1)
	v_mfma_f32_32x32x16_bf16 v[80:95], v[232:235], v[96:99], v[80:95]
	v_mov_b32_e32 v232, v231
	s_nop 1
	v_permlane32_swap_b32_e32 v231, v232
	v_permlane32_swap_b32_e32 v160, v162
	v_cvt_pk_bf16_f32 v166, v166, v169
	v_cvt_pk_bf16_f32 v167, v167, v170
	s_waitcnt lgkmcnt(0)
	v_mfma_f32_32x32x16_bf16 v[64:79], v[236:239], v[96:99], v[64:79]
	v_cvt_pk_bf16_f32 v170, v158, v159
	v_cvt_pk_bf16_f32 v171, v156, v157
	v_cvt_pk_bf16_f32 v172, v152, v153
	v_cvt_pk_bf16_f32 v173, v148, v149
	v_cvt_pk_bf16_f32 v234, v144, v145
	v_cvt_pk_bf16_f32 v235, v154, v155
	v_cvt_pk_bf16_f32 v236, v150, v151
	v_cvt_pk_bf16_f32 v237, v146, v147
	v_permlane32_swap_b32_e32 v161, v163
	v_permlane32_swap_b32_e32 v164, v166
	v_permlane32_swap_b32_e32 v165, v167
	v_permlane32_swap_b32_e32 v170, v172
	v_permlane32_swap_b32_e32 v171, v173
	v_permlane32_swap_b32_e32 v234, v236
	v_permlane32_swap_b32_e32 v235, v237
	v_lshl_add_u64 v[188:189], v[184:185], 0, v[178:179]
	s_mov_b32 s8, 0x18000
	v_add_co_u32_e32 v144, vcc, s8, v188
	s_mov_b32 s9, 0x1c000
	s_nop 0
	v_addc_co_u32_e32 v145, vcc, 0, v189, vcc
	v_add_co_u32_e32 v148, vcc, s9, v188
	v_lshl_add_u64 v[186:187], v[182:183], 0, v[178:179]
	s_nop 0
	v_addc_co_u32_e32 v149, vcc, 0, v189, vcc
	v_add_co_u32_e32 v152, vcc, s8, v186
	global_load_dwordx4 v[144:147], v[144:145], off
	s_nop 0
	global_load_dwordx4 v[148:151], v[148:149], off
	v_addc_co_u32_e32 v153, vcc, 0, v187, vcc
	v_add_co_u32_e32 v156, vcc, s9, v186
	s_nop 1
	v_addc_co_u32_e32 v157, vcc, 0, v187, vcc
	global_load_dwordx4 v[152:155], v[152:153], off
	s_nop 0
	global_load_dwordx4 v[156:159], v[156:157], off
	ds_read_b64_tr_b16 v[238:239], v194 offset:0
	ds_read_b64_tr_b16 v[240:241], v194 offset:0x800
	ds_read_b64_tr_b16 v[242:243], v194 offset:0x1000
	ds_read_b64_tr_b16 v[244:245], v194 offset:0x1800
	ds_read_b64_tr_b16 v[246:247], v194 offset:0x2000
	ds_read_b64_tr_b16 v[248:249], v194 offset:0x2800
	ds_read_b64_tr_b16 v[212:213], v194 offset:0x3000
	ds_read_b64_tr_b16 v[214:215], v194 offset:0x3800
	s_nop 0
	s_waitcnt lgkmcnt(6)
	v_mfma_f32_32x32x16_bf16 v[0:15], v[160:163], v[238:241], v[0:15]
	s_waitcnt lgkmcnt(4)
	v_mfma_f32_32x32x16_bf16 v[0:15], v[164:167], v[242:245], v[0:15]
	s_waitcnt lgkmcnt(2)
	v_mfma_f32_32x32x16_bf16 v[0:15], v[170:173], v[246:249], v[0:15]
	s_waitcnt lgkmcnt(0)
	v_mfma_f32_32x32x16_bf16 v[0:15], v[234:237], v[212:215], v[0:15]
	ds_read_b64_tr_b16 v[212:213], v194 offset:0x200
	ds_read_b64_tr_b16 v[214:215], v194 offset:0xa00
	ds_read_b64_tr_b16 v[238:239], v194 offset:0x1200
	ds_read_b64_tr_b16 v[240:241], v194 offset:0x1a00
	ds_read_b64_tr_b16 v[242:243], v194 offset:0x2200
	ds_read_b64_tr_b16 v[244:245], v194 offset:0x2a00
	ds_read_b64_tr_b16 v[246:247], v194 offset:0x3200
	ds_read_b64_tr_b16 v[248:249], v194 offset:0x3a00
	s_nop 0
	s_waitcnt lgkmcnt(6)
	v_mfma_f32_32x32x16_bf16 v[48:63], v[160:163], v[212:215], v[48:63]
	ds_read_b64_tr_b16 v[212:213], v194 offset:0x400
	ds_read_b64_tr_b16 v[214:215], v194 offset:0xc00
	s_waitcnt lgkmcnt(6)
	v_mfma_f32_32x32x16_bf16 v[48:63], v[164:167], v[238:241], v[48:63]
	ds_read_b64_tr_b16 v[238:239], v194 offset:0x1400
	ds_read_b64_tr_b16 v[240:241], v194 offset:0x1c00
	s_waitcnt lgkmcnt(6)
	v_mfma_f32_32x32x16_bf16 v[48:63], v[170:173], v[242:245], v[48:63]
	ds_read_b64_tr_b16 v[242:243], v194 offset:0x2400
	ds_read_b64_tr_b16 v[244:245], v194 offset:0x2c00
	s_waitcnt lgkmcnt(6)
	v_mfma_f32_32x32x16_bf16 v[48:63], v[234:237], v[246:249], v[48:63]
	ds_read_b64_tr_b16 v[246:247], v194 offset:0x3400
	ds_read_b64_tr_b16 v[248:249], v194 offset:0x3c00
	s_waitcnt lgkmcnt(6)
	v_mfma_f32_32x32x16_bf16 v[32:47], v[160:163], v[212:215], v[32:47]
	ds_read_b64_tr_b16 v[212:213], v194 offset:0x600
	ds_read_b64_tr_b16 v[214:215], v194 offset:0xe00
	s_waitcnt lgkmcnt(6)
	v_mfma_f32_32x32x16_bf16 v[32:47], v[164:167], v[238:241], v[32:47]
	ds_read_b64_tr_b16 v[238:239], v194 offset:0x1600
	ds_read_b64_tr_b16 v[240:241], v194 offset:0x1e00
	s_waitcnt lgkmcnt(6)
	v_mfma_f32_32x32x16_bf16 v[32:47], v[170:173], v[242:245], v[32:47]
	ds_read_b64_tr_b16 v[242:243], v194 offset:0x2600
	ds_read_b64_tr_b16 v[244:245], v194 offset:0x2e00
	s_waitcnt lgkmcnt(6)
	v_mfma_f32_32x32x16_bf16 v[32:47], v[234:237], v[246:249], v[32:47]
	ds_read_b64_tr_b16 v[246:247], v194 offset:0x3600
	ds_read_b64_tr_b16 v[248:249], v194 offset:0x3e00
	s_waitcnt lgkmcnt(6)
	v_mfma_f32_32x32x16_bf16 v[16:31], v[160:163], v[212:215], v[16:31]
	v_max_f32_e32 v160, v81, v81
	v_max_f32_e32 v161, v80, v80
	v_max_f32_e32 v160, v161, v160
	v_max3_f32 v160, v160, v82, v83
	v_max3_f32 v160, v160, v84, v85
	v_max3_f32 v160, v160, v86, v87
	v_max3_f32 v160, v160, v88, v89
	v_max3_f32 v160, v160, v90, v91
	v_max3_f32 v160, v160, v92, v93
	s_waitcnt lgkmcnt(4)
	v_mfma_f32_32x32x16_bf16 v[16:31], v[164:167], v[238:241], v[16:31]
	v_max3_f32 v160, v160, v94, v95
	v_max3_f32 v160, v160, v64, v65
	v_max3_f32 v160, v160, v66, v67
	v_max3_f32 v160, v160, v68, v69
	v_max3_f32 v160, v160, v70, v71
	v_max3_f32 v160, v160, v72, v73
	v_max3_f32 v160, v160, v74, v75
	v_max3_f32 v160, v160, v76, v77
	s_waitcnt lgkmcnt(2)
	v_mfma_f32_32x32x16_bf16 v[16:31], v[170:173], v[242:245], v[16:31]
	v_max3_f32 v160, v160, v78, v79
	v_mov_b32_e32 v161, v160
	s_nop 1
	v_permlane32_swap_b32_e32 v160, v161
	v_max_f32_e32 v161, v161, v161
	v_max_f32_e32 v160, v160, v160
	v_max_f32_e32 v160, v160, v161
	v_sub_f32_e32 v161, v160, v168
	s_mov_b32 s8, 0x42b504f3
	v_cmp_ge_f32_e32 vcc, s8, v161
	v_max_f32_e32 v161, v168, v168
	v_max_f32_e32 v160, v161, v160
	s_waitcnt lgkmcnt(0)
	v_mfma_f32_32x32x16_bf16 v[16:31], v[234:237], v[246:249], v[16:31]
	v_sub_f32_e32 v161, v168, v160
	v_mul_f32_e32 v161, 0x3e0293ee, v161
	v_exp_f32_e32 v161, v161
	s_cmp_eq_u64 vcc, exec
	s_cselect_b64 s[8:9], -1, 0
	s_waitcnt lgkmcnt(0)
	s_barrier
	s_waitcnt vmcnt(4)
	v_cndmask_b32_e64 v233, v161, 1.0, s[8:9]
	v_cmp_gt_f32_e32 vcc, 1.0, v233
	ds_write_b128 v198, v[128:131]
	ds_write_b128 v199, v[132:135]
	ds_write_b128 v196, v[136:139] offset:32768
	ds_write_b128 v197, v[140:143] offset:32768
	s_cbranch_vccz .LBB0_962
	s_and_saveexec_b64 s[16:17], s[6:7]
	ds_write_b32 v191, v233 offset:128
	s_or_b64 exec, exec, s[16:17]
	s_waitcnt lgkmcnt(0)
	v_add_u32_e32 v161, v181, v176
	ds_read_b128 v[162:165], v161 offset:224
	ds_read_b128 v[170:173], v161 offset:192
	ds_read_b128 v[212:215], v161 offset:160
	ds_read_b128 v[234:237], v161 offset:128
	s_waitcnt lgkmcnt(0)
	v_pk_mul_f32 v[12:13], v[12:13], v[162:163]
	v_pk_mul_f32 v[8:9], v[8:9], v[170:171]
	v_pk_mul_f32 v[4:5], v[4:5], v[212:213]
	v_pk_mul_f32 v[14:15], v[14:15], v[164:165]
	v_pk_mul_f32 v[10:11], v[10:11], v[172:173]
	v_pk_mul_f32 v[6:7], v[6:7], v[214:215]
	v_pk_mul_f32 v[2:3], v[2:3], v[236:237]
	v_pk_mul_f32 v[0:1], v[0:1], v[234:235]
	v_pk_mul_f32 v[60:61], v[60:61], v[162:163]
	v_pk_mul_f32 v[56:57], v[56:57], v[170:171]
	v_pk_mul_f32 v[52:53], v[52:53], v[212:213]
	v_pk_mul_f32 v[62:63], v[62:63], v[164:165]
	v_pk_mul_f32 v[58:59], v[58:59], v[172:173]
	v_pk_mul_f32 v[54:55], v[54:55], v[214:215]
	v_pk_mul_f32 v[50:51], v[50:51], v[236:237]
	v_pk_mul_f32 v[48:49], v[48:49], v[234:235]
	v_pk_mul_f32 v[44:45], v[44:45], v[162:163]
	v_pk_mul_f32 v[40:41], v[40:41], v[170:171]
	v_pk_mul_f32 v[36:37], v[36:37], v[212:213]
	v_pk_mul_f32 v[46:47], v[46:47], v[164:165]
	v_pk_mul_f32 v[42:43], v[42:43], v[172:173]
	v_pk_mul_f32 v[38:39], v[38:39], v[214:215]
	v_pk_mul_f32 v[34:35], v[34:35], v[236:237]
	v_pk_mul_f32 v[32:33], v[32:33], v[234:235]
	v_pk_mul_f32 v[28:29], v[28:29], v[162:163]
	v_pk_mul_f32 v[24:25], v[24:25], v[170:171]
	v_pk_mul_f32 v[20:21], v[20:21], v[212:213]
	v_pk_mul_f32 v[30:31], v[30:31], v[164:165]
	v_pk_mul_f32 v[26:27], v[26:27], v[172:173]
	v_pk_mul_f32 v[22:23], v[22:23], v[214:215]
	v_pk_mul_f32 v[18:19], v[18:19], v[236:237]
	v_pk_mul_f32 v[16:17], v[16:17], v[234:235]

.LBB0_964:
	ds_read_b64_tr_b16 v[186:187], v193 offset:0
	ds_read_b64_tr_b16 v[188:189], v193 offset:0x800
	ds_read_b64_tr_b16 v[204:205], v193 offset:0x1000
	ds_read_b64_tr_b16 v[206:207], v193 offset:0x1800
	ds_read_b64_tr_b16 v[212:213], v193 offset:0x2000
	ds_read_b64_tr_b16 v[214:215], v193 offset:0x2800
	ds_read_b64_tr_b16 v[238:239], v193 offset:0x3000
	ds_read_b64_tr_b16 v[240:241], v193 offset:0x3800
	s_nop 0
	s_waitcnt lgkmcnt(6)
	v_mfma_f32_32x32x16_bf16 v[0:15], v[160:163], v[186:189], v[0:15]
	ds_read_b64_tr_b16 v[186:187], v193 offset:0x200
	ds_read_b64_tr_b16 v[188:189], v193 offset:0xa00
	s_waitcnt lgkmcnt(6)
	v_mfma_f32_32x32x16_bf16 v[0:15], v[164:167], v[204:207], v[0:15]
	ds_read_b64_tr_b16 v[204:205], v193 offset:0x1200
	ds_read_b64_tr_b16 v[206:207], v193 offset:0x1a00
	s_waitcnt lgkmcnt(6)
	v_mfma_f32_32x32x16_bf16 v[0:15], v[168:171], v[212:215], v[0:15]
	ds_read_b64_tr_b16 v[212:213], v193 offset:0x2200
	ds_read_b64_tr_b16 v[214:215], v193 offset:0x2a00
	s_waitcnt lgkmcnt(6)
	v_mfma_f32_32x32x16_bf16 v[0:15], v[172:175], v[238:241], v[0:15]
	ds_read_b64_tr_b16 v[238:239], v193 offset:0x3200
	ds_read_b64_tr_b16 v[240:241], v193 offset:0x3a00
	s_waitcnt lgkmcnt(6)
	v_mfma_f32_32x32x16_bf16 v[48:63], v[160:163], v[186:189], v[48:63]
	ds_read_b64_tr_b16 v[186:187], v193 offset:0x400
	ds_read_b64_tr_b16 v[188:189], v193 offset:0xc00
	s_waitcnt lgkmcnt(6)
	v_mfma_f32_32x32x16_bf16 v[48:63], v[164:167], v[204:207], v[48:63]
	ds_read_b64_tr_b16 v[204:205], v193 offset:0x1400
	ds_read_b64_tr_b16 v[206:207], v193 offset:0x1c00
	s_waitcnt lgkmcnt(6)
	v_mfma_f32_32x32x16_bf16 v[48:63], v[168:171], v[212:215], v[48:63]
	ds_read_b64_tr_b16 v[212:213], v193 offset:0x2400
	ds_read_b64_tr_b16 v[214:215], v193 offset:0x2c00
	s_waitcnt lgkmcnt(6)
	v_mfma_f32_32x32x16_bf16 v[48:63], v[172:175], v[238:241], v[48:63]
	ds_read_b64_tr_b16 v[238:239], v193 offset:0x3400
	ds_read_b64_tr_b16 v[240:241], v193 offset:0x3c00
	s_waitcnt lgkmcnt(6)
	v_mfma_f32_32x32x16_bf16 v[32:47], v[160:163], v[186:189], v[32:47]
	ds_read_b64_tr_b16 v[186:187], v193 offset:0x600
	ds_read_b64_tr_b16 v[188:189], v193 offset:0xe00
	s_waitcnt lgkmcnt(6)
	v_mfma_f32_32x32x16_bf16 v[32:47], v[164:167], v[204:207], v[32:47]
	ds_read_b64_tr_b16 v[204:205], v193 offset:0x1600
	ds_read_b64_tr_b16 v[206:207], v193 offset:0x1e00
	s_waitcnt lgkmcnt(6)
	v_mfma_f32_32x32x16_bf16 v[32:47], v[168:171], v[212:215], v[32:47]
	ds_read_b64_tr_b16 v[212:213], v193 offset:0x2600
	ds_read_b64_tr_b16 v[214:215], v193 offset:0x2e00
	s_waitcnt lgkmcnt(6)
	v_mfma_f32_32x32x16_bf16 v[32:47], v[172:175], v[238:241], v[32:47]
	ds_read_b64_tr_b16 v[238:239], v193 offset:0x3600
	ds_read_b64_tr_b16 v[240:241], v193 offset:0x3e00
	s_waitcnt lgkmcnt(6)
	v_mfma_f32_32x32x16_bf16 v[16:31], v[160:163], v[186:189], v[16:31]
	v_max_f32_e32 v160, v81, v81
	v_max_f32_e32 v161, v80, v80
	v_max_f32_e32 v160, v161, v160
	v_max3_f32 v160, v160, v82, v83
	v_max3_f32 v160, v160, v84, v85
	v_max3_f32 v160, v160, v86, v87
	v_max3_f32 v160, v160, v88, v89
	v_max3_f32 v160, v160, v90, v91
	v_max3_f32 v160, v160, v92, v93
	s_waitcnt lgkmcnt(4)
	v_mfma_f32_32x32x16_bf16 v[16:31], v[164:167], v[204:207], v[16:31]
	v_max3_f32 v160, v160, v94, v95
	v_max3_f32 v160, v160, v64, v65
	v_max3_f32 v160, v160, v66, v67
	v_max3_f32 v160, v160, v68, v69
	v_max3_f32 v160, v160, v70, v71
	v_max3_f32 v160, v160, v72, v73
	v_max3_f32 v160, v160, v74, v75
	v_max3_f32 v160, v160, v76, v77
	s_waitcnt lgkmcnt(2)
	v_mfma_f32_32x32x16_bf16 v[16:31], v[168:171], v[212:215], v[16:31]
	v_max3_f32 v160, v160, v78, v79
	v_mov_b32_e32 v161, v160
	s_nop 1
	v_permlane32_swap_b32_e32 v160, v161
	v_max_f32_e32 v161, v161, v161
	v_max_f32_e32 v160, v160, v160
	v_max_f32_e32 v160, v160, v161
	v_sub_f32_e32 v161, v160, v234
	s_mov_b32 s8, 0x42b504f3
	v_cmp_ge_f32_e32 vcc, s8, v161
	v_max_f32_e32 v161, v234, v234
	v_max_f32_e32 v161, v161, v160
	s_waitcnt lgkmcnt(0)
	v_mfma_f32_32x32x16_bf16 v[16:31], v[172:175], v[238:241], v[16:31]
	v_sub_f32_e32 v160, v234, v161
	v_mul_f32_e32 v160, 0x3e0293ee, v160
	v_exp_f32_e32 v160, v160
	s_cmp_eq_u64 vcc, exec
	s_cselect_b64 s[8:9], -1, 0
	s_waitcnt lgkmcnt(0)
	s_barrier
	s_waitcnt vmcnt(4)
	v_cndmask_b32_e64 v160, v160, 1.0, s[8:9]
	v_cmp_gt_f32_e32 vcc, 1.0, v160
	s_waitcnt vmcnt(0)
	ds_write_b128 v198, v[144:147] offset:16384
	ds_write_b128 v199, v[148:151] offset:16384
	ds_write_b128 v196, v[152:155] offset:49152
	ds_write_b128 v197, v[156:159] offset:49152
	s_cbranch_vccz .LBB0_968
	s_and_saveexec_b64 s[18:19], s[6:7]
	ds_write_b32 v191, v160 offset:128
	s_or_b64 exec, exec, s[18:19]
	s_waitcnt lgkmcnt(0)
	v_add_u32_e32 v156, v181, v176
	ds_read_b128 v[144:147], v156 offset:224
	ds_read_b128 v[148:151], v156 offset:192
	ds_read_b128 v[152:155], v156 offset:160
	ds_read_b128 v[156:159], v156 offset:128
	s_waitcnt lgkmcnt(3)
	v_pk_mul_f32 v[12:13], v[12:13], v[144:145]
	s_waitcnt lgkmcnt(2)
	v_pk_mul_f32 v[8:9], v[8:9], v[148:149]
	s_waitcnt lgkmcnt(1)
	v_pk_mul_f32 v[4:5], v[4:5], v[152:153]
	v_pk_mul_f32 v[14:15], v[14:15], v[146:147]
	v_pk_mul_f32 v[10:11], v[10:11], v[150:151]
	v_pk_mul_f32 v[6:7], v[6:7], v[154:155]
	s_waitcnt lgkmcnt(0)
	v_pk_mul_f32 v[2:3], v[2:3], v[158:159]
	v_pk_mul_f32 v[0:1], v[0:1], v[156:157]
	v_pk_mul_f32 v[60:61], v[60:61], v[144:145]
	v_pk_mul_f32 v[56:57], v[56:57], v[148:149]
	v_pk_mul_f32 v[52:53], v[52:53], v[152:153]
	v_pk_mul_f32 v[62:63], v[62:63], v[146:147]
	v_pk_mul_f32 v[58:59], v[58:59], v[150:151]
	v_pk_mul_f32 v[54:55], v[54:55], v[154:155]
	v_pk_mul_f32 v[50:51], v[50:51], v[158:159]
	v_pk_mul_f32 v[48:49], v[48:49], v[156:157]
	v_pk_mul_f32 v[44:45], v[44:45], v[144:145]
	v_pk_mul_f32 v[40:41], v[40:41], v[148:149]
	v_pk_mul_f32 v[36:37], v[36:37], v[152:153]
	v_pk_mul_f32 v[46:47], v[46:47], v[146:147]
	v_pk_mul_f32 v[42:43], v[42:43], v[150:151]
	v_pk_mul_f32 v[38:39], v[38:39], v[154:155]
	v_pk_mul_f32 v[34:35], v[34:35], v[158:159]
	v_pk_mul_f32 v[32:33], v[32:33], v[156:157]
	v_pk_mul_f32 v[28:29], v[28:29], v[144:145]
	v_pk_mul_f32 v[24:25], v[24:25], v[148:149]
	v_pk_mul_f32 v[20:21], v[20:21], v[152:153]
	v_pk_mul_f32 v[30:31], v[30:31], v[146:147]
	v_pk_mul_f32 v[26:27], v[26:27], v[150:151]
	v_pk_mul_f32 v[22:23], v[22:23], v[154:155]
	v_pk_mul_f32 v[18:19], v[18:19], v[158:159]
	v_pk_mul_f32 v[16:17], v[16:17], v[156:157]

.LBB0_970:
	ds_read_b128 v[64:67], v195 offset:49152
	ds_read_b128 v[68:71], v195 offset:57344
	s_waitcnt lgkmcnt(1)
	v_mfma_f32_32x32x16_bf16 v[80:95], v[64:67], v[112:115], 0
	s_waitcnt lgkmcnt(0)
	v_mfma_f32_32x32x16_bf16 v[64:79], v[68:71], v[112:115], 0
	ds_read_b128 v[112:115], v226 offset:49152
	ds_read_b128 v[128:131], v226 offset:57344
	s_waitcnt lgkmcnt(1)
	v_mfma_f32_32x32x16_bf16 v[80:95], v[112:115], v[108:111], v[80:95]
	s_waitcnt lgkmcnt(0)
	v_mfma_f32_32x32x16_bf16 v[64:79], v[128:131], v[108:111], v[64:79]
	ds_read_b128 v[108:111], v225 offset:49152
	ds_read_b128 v[112:115], v225 offset:57344
	s_waitcnt lgkmcnt(1)
	v_mfma_f32_32x32x16_bf16 v[80:95], v[108:111], v[120:123], v[80:95]
	s_waitcnt lgkmcnt(0)
	v_mfma_f32_32x32x16_bf16 v[64:79], v[112:115], v[120:123], v[64:79]
	ds_read_b128 v[108:111], v224 offset:49152
	ds_read_b128 v[112:115], v224 offset:57344
	v_exp_f32_e32 v120, v146
	v_exp_f32_e32 v121, v147
	s_waitcnt lgkmcnt(1)
	v_mfma_f32_32x32x16_bf16 v[80:95], v[108:111], v[124:127], v[80:95]
	s_waitcnt lgkmcnt(0)
	v_mfma_f32_32x32x16_bf16 v[64:79], v[112:115], v[124:127], v[64:79]
	ds_read_b128 v[108:111], v223 offset:49152
	ds_read_b128 v[112:115], v223 offset:57344
	s_waitcnt lgkmcnt(1)
	v_mfma_f32_32x32x16_bf16 v[80:95], v[108:111], v[116:119], v[80:95]
	s_waitcnt lgkmcnt(0)
	v_mfma_f32_32x32x16_bf16 v[64:79], v[112:115], v[116:119], v[64:79]
	ds_read_b128 v[108:111], v227 offset:49152
	ds_read_b128 v[112:115], v227 offset:57344
	v_exp_f32_e32 v116, v154
	v_exp_f32_e32 v117, v155
	v_exp_f32_e32 v118, v150
	v_exp_f32_e32 v119, v151
	s_waitcnt lgkmcnt(1)
	v_mfma_f32_32x32x16_bf16 v[80:95], v[108:111], v[104:107], v[80:95]
	s_waitcnt lgkmcnt(0)
	v_mfma_f32_32x32x16_bf16 v[64:79], v[112:115], v[104:107], v[64:79]
	ds_read_b128 v[104:107], v228 offset:49152
	ds_read_b128 v[108:111], v228 offset:57344
	v_exp_f32_e32 v112, v148
	v_exp_f32_e32 v113, v149
	v_exp_f32_e32 v114, v144
	v_exp_f32_e32 v115, v145
	s_waitcnt lgkmcnt(1)
	v_mfma_f32_32x32x16_bf16 v[80:95], v[104:107], v[100:103], v[80:95]
	s_waitcnt lgkmcnt(0)
	v_mfma_f32_32x32x16_bf16 v[64:79], v[108:111], v[100:103], v[64:79]
	ds_read_b128 v[100:103], v229 offset:49152
	ds_read_b128 v[104:107], v229 offset:57344
	v_exp_f32_e32 v108, v156
	v_exp_f32_e32 v109, v157
	v_exp_f32_e32 v110, v152
	v_exp_f32_e32 v111, v153
	s_waitcnt lgkmcnt(1)
	v_mfma_f32_32x32x16_bf16 v[80:95], v[100:103], v[96:99], v[80:95]
	s_waitcnt lgkmcnt(0)
	v_mfma_f32_32x32x16_bf16 v[64:79], v[104:107], v[96:99], v[64:79]
	v_add_f32_e32 v96, 0, v161
	v_add_f32_e32 v96, v175, v96
	v_add_f32_e32 v96, v162, v96
	v_add_f32_e32 v96, v186, v96
	v_add_f32_e32 v96, v174, v96
	v_add_f32_e32 v96, v187, v96
	v_add_f32_e32 v96, v163, v96
	v_add_f32_e32 v96, v173, v96
	v_add_f32_e32 v96, v164, v96
	v_add_f32_e32 v96, v171, v96
	v_add_f32_e32 v96, v165, v96
	v_add_f32_e32 v96, v172, v96
	v_exp_f32_e32 v106, v158
	v_add_f32_e32 v96, v166, v96
	v_exp_f32_e32 v107, v159
	v_add_f32_e32 v96, v169, v96
	v_add_f32_e32 v96, v167, v96
	v_add_f32_e32 v96, v170, v96
	v_add_f32_e32 v96, v106, v96
	v_add_f32_e32 v96, v107, v96
	v_add_f32_e32 v96, v108, v96
	v_add_f32_e32 v96, v109, v96
	v_add_f32_e32 v96, v110, v96
	v_add_f32_e32 v96, v111, v96
	v_add_f32_e32 v96, v112, v96
	v_add_f32_e32 v96, v113, v96
	v_add_f32_e32 v96, v114, v96
	v_add_f32_e32 v96, v115, v96
	v_add_f32_e32 v96, v116, v96
	v_add_f32_e32 v96, v117, v96
	v_add_f32_e32 v96, v118, v96
	v_add_f32_e32 v96, v119, v96
	v_add_f32_e32 v96, v120, v96
	v_add_f32_e32 v100, v121, v96
	v_mov_b32_e32 v101, v100
	v_cvt_pk_bf16_f32 v96, v161, v175
	v_cvt_pk_bf16_f32 v97, v162, v186
	v_cvt_pk_bf16_f32 v98, v174, v187
	v_cvt_pk_bf16_f32 v99, v163, v173
	s_nop 1
	v_permlane32_swap_b32_e32 v100, v101
	v_permlane32_swap_b32_e32 v96, v98
	v_permlane32_swap_b32_e32 v97, v99
	v_cvt_pk_bf16_f32 v102, v164, v171
	v_cvt_pk_bf16_f32 v103, v165, v172
	v_cvt_pk_bf16_f32 v104, v166, v169
	v_cvt_pk_bf16_f32 v105, v167, v170
	v_cvt_pk_bf16_f32 v106, v106, v107
	v_cvt_pk_bf16_f32 v107, v108, v109
	v_cvt_pk_bf16_f32 v108, v110, v111
	v_cvt_pk_bf16_f32 v109, v112, v113
	v_cvt_pk_bf16_f32 v110, v114, v115
	v_cvt_pk_bf16_f32 v111, v116, v117
	v_cvt_pk_bf16_f32 v112, v118, v119
	v_cvt_pk_bf16_f32 v113, v120, v121
	s_nop 0
	v_permlane32_swap_b32_e32 v102, v104
	v_permlane32_swap_b32_e32 v103, v105
	v_permlane32_swap_b32_e32 v106, v108
	v_permlane32_swap_b32_e32 v107, v109
	v_permlane32_swap_b32_e32 v110, v112
	v_permlane32_swap_b32_e32 v111, v113
	ds_read_b64_tr_b16 v[114:115], v194 offset:0
	ds_read_b64_tr_b16 v[116:117], v194 offset:0x800
	ds_read_b64_tr_b16 v[118:119], v194 offset:0x1000
	ds_read_b64_tr_b16 v[120:121], v194 offset:0x1800
	ds_read_b64_tr_b16 v[122:123], v194 offset:0x2000
	ds_read_b64_tr_b16 v[124:125], v194 offset:0x2800
	ds_read_b64_tr_b16 v[126:127], v194 offset:0x3000
	ds_read_b64_tr_b16 v[128:129], v194 offset:0x3800
	s_nop 0
	s_waitcnt lgkmcnt(6)
	v_mfma_f32_32x32x16_bf16 v[0:15], v[96:99], v[114:117], v[0:15]
	ds_read_b64_tr_b16 v[114:115], v194 offset:0x200
	ds_read_b64_tr_b16 v[116:117], v194 offset:0xa00
	s_waitcnt lgkmcnt(6)
	v_mfma_f32_32x32x16_bf16 v[0:15], v[102:105], v[118:121], v[0:15]
	ds_read_b64_tr_b16 v[118:119], v194 offset:0x1200
	ds_read_b64_tr_b16 v[120:121], v194 offset:0x1a00
	s_waitcnt lgkmcnt(6)
	v_mfma_f32_32x32x16_bf16 v[0:15], v[106:109], v[122:125], v[0:15]
	ds_read_b64_tr_b16 v[122:123], v194 offset:0x2200
	ds_read_b64_tr_b16 v[124:125], v194 offset:0x2a00
	s_waitcnt lgkmcnt(6)
	v_mfma_f32_32x32x16_bf16 v[0:15], v[110:113], v[126:129], v[0:15]
	ds_read_b64_tr_b16 v[126:127], v194 offset:0x3200
	ds_read_b64_tr_b16 v[128:129], v194 offset:0x3a00
	s_waitcnt lgkmcnt(6)
	v_mfma_f32_32x32x16_bf16 v[48:63], v[96:99], v[114:117], v[48:63]
	ds_read_b64_tr_b16 v[114:115], v194 offset:0x400
	ds_read_b64_tr_b16 v[116:117], v194 offset:0xc00
	s_waitcnt lgkmcnt(6)
	v_mfma_f32_32x32x16_bf16 v[48:63], v[102:105], v[118:121], v[48:63]
	ds_read_b64_tr_b16 v[118:119], v194 offset:0x1400
	ds_read_b64_tr_b16 v[120:121], v194 offset:0x1c00
	s_waitcnt lgkmcnt(6)
	v_mfma_f32_32x32x16_bf16 v[48:63], v[106:109], v[122:125], v[48:63]
	ds_read_b64_tr_b16 v[122:123], v194 offset:0x2400
	ds_read_b64_tr_b16 v[124:125], v194 offset:0x2c00
	s_waitcnt lgkmcnt(6)
	v_mfma_f32_32x32x16_bf16 v[48:63], v[110:113], v[126:129], v[48:63]
	ds_read_b64_tr_b16 v[126:127], v194 offset:0x3400
	ds_read_b64_tr_b16 v[128:129], v194 offset:0x3c00
	s_waitcnt lgkmcnt(6)
	v_mfma_f32_32x32x16_bf16 v[32:47], v[96:99], v[114:117], v[32:47]
	ds_read_b64_tr_b16 v[114:115], v194 offset:0x600
	ds_read_b64_tr_b16 v[116:117], v194 offset:0xe00
	s_waitcnt lgkmcnt(6)
	v_mfma_f32_32x32x16_bf16 v[32:47], v[102:105], v[118:121], v[32:47]
	ds_read_b64_tr_b16 v[118:119], v194 offset:0x1600
	ds_read_b64_tr_b16 v[120:121], v194 offset:0x1e00
	s_waitcnt lgkmcnt(6)
	v_mfma_f32_32x32x16_bf16 v[32:47], v[106:109], v[122:125], v[32:47]
	ds_read_b64_tr_b16 v[122:123], v194 offset:0x2600
	ds_read_b64_tr_b16 v[124:125], v194 offset:0x2e00
	s_waitcnt lgkmcnt(6)
	v_mfma_f32_32x32x16_bf16 v[32:47], v[110:113], v[126:129], v[32:47]
	ds_read_b64_tr_b16 v[126:127], v194 offset:0x3600
	ds_read_b64_tr_b16 v[128:129], v194 offset:0x3e00
	s_waitcnt lgkmcnt(6)
	v_mfma_f32_32x32x16_bf16 v[16:31], v[96:99], v[114:117], v[16:31]
	v_max_f32_e32 v96, v81, v81
	v_max_f32_e32 v97, v80, v80
	v_max_f32_e32 v96, v97, v96
	v_max3_f32 v96, v96, v82, v83
	v_max3_f32 v96, v96, v84, v85
	v_max3_f32 v96, v96, v86, v87
	v_max3_f32 v96, v96, v88, v89
	v_max3_f32 v96, v96, v90, v91
	v_max3_f32 v96, v96, v92, v93
	s_waitcnt lgkmcnt(4)
	v_mfma_f32_32x32x16_bf16 v[16:31], v[102:105], v[118:121], v[16:31]
	v_max3_f32 v96, v96, v94, v95
	v_max3_f32 v96, v96, v64, v65
	v_max3_f32 v96, v96, v66, v67
	v_max3_f32 v96, v96, v68, v69
	v_max3_f32 v96, v96, v70, v71
	v_max3_f32 v96, v96, v72, v73
	v_max3_f32 v96, v96, v74, v75
	v_max3_f32 v96, v96, v76, v77
	s_waitcnt lgkmcnt(2)
	v_mfma_f32_32x32x16_bf16 v[16:31], v[106:109], v[122:125], v[16:31]
	v_max3_f32 v96, v96, v78, v79
	v_mov_b32_e32 v97, v96
	s_nop 1
	v_permlane32_swap_b32_e32 v96, v97
	v_max_f32_e32 v97, v97, v97
	v_max_f32_e32 v96, v96, v96
	v_max_f32_e32 v96, v96, v97
	v_sub_f32_e32 v97, v96, v168
	s_mov_b32 s8, 0x42b504f3
	v_cmp_ge_f32_e32 vcc, s8, v97
	v_max_f32_e32 v97, v168, v168
	v_max_f32_e32 v97, v97, v96
	s_waitcnt lgkmcnt(0)
	v_mfma_f32_32x32x16_bf16 v[16:31], v[110:113], v[126:129], v[16:31]
	v_sub_f32_e32 v96, v168, v97
	v_mul_f32_e32 v96, 0x3e0293ee, v96
	v_exp_f32_e32 v96, v96
	s_cmp_eq_u64 vcc, exec
	s_cselect_b64 s[8:9], -1, 0
	v_cndmask_b32_e64 v96, v96, 1.0, s[8:9]
	v_cmp_gt_f32_e32 vcc, 1.0, v96
	s_barrier
	s_cbranch_vccz .LBB0_974
	s_and_saveexec_b64 s[16:17], s[6:7]
	ds_write_b32 v191, v96 offset:128
	s_or_b64 exec, exec, s[16:17]
	s_waitcnt lgkmcnt(0)
	v_add_u32_e32 v98, v181, v176
	ds_read_b128 v[102:105], v98 offset:224
	ds_read_b128 v[106:109], v98 offset:192
	ds_read_b128 v[110:113], v98 offset:160
	ds_read_b128 v[114:117], v98 offset:128
	s_waitcnt lgkmcnt(3)
	v_pk_mul_f32 v[12:13], v[12:13], v[102:103]
	s_waitcnt lgkmcnt(2)
	v_pk_mul_f32 v[8:9], v[8:9], v[106:107]
	s_waitcnt lgkmcnt(1)
	v_pk_mul_f32 v[4:5], v[4:5], v[110:111]
	v_pk_mul_f32 v[14:15], v[14:15], v[104:105]
	v_pk_mul_f32 v[10:11], v[10:11], v[108:109]
	v_pk_mul_f32 v[6:7], v[6:7], v[112:113]
	s_waitcnt lgkmcnt(0)
	v_pk_mul_f32 v[2:3], v[2:3], v[116:117]
	v_pk_mul_f32 v[0:1], v[0:1], v[114:115]
	v_pk_mul_f32 v[60:61], v[60:61], v[102:103]
	v_pk_mul_f32 v[56:57], v[56:57], v[106:107]
	v_pk_mul_f32 v[52:53], v[52:53], v[110:111]
	v_pk_mul_f32 v[62:63], v[62:63], v[104:105]
	v_pk_mul_f32 v[58:59], v[58:59], v[108:109]
	v_pk_mul_f32 v[54:55], v[54:55], v[112:113]
	v_pk_mul_f32 v[50:51], v[50:51], v[116:117]
	v_pk_mul_f32 v[48:49], v[48:49], v[114:115]
	v_pk_mul_f32 v[44:45], v[44:45], v[102:103]
	v_pk_mul_f32 v[40:41], v[40:41], v[106:107]
	v_pk_mul_f32 v[36:37], v[36:37], v[110:111]
	v_pk_mul_f32 v[46:47], v[46:47], v[104:105]
	v_pk_mul_f32 v[42:43], v[42:43], v[108:109]
	v_pk_mul_f32 v[38:39], v[38:39], v[112:113]
	v_pk_mul_f32 v[34:35], v[34:35], v[116:117]
	v_pk_mul_f32 v[32:33], v[32:33], v[114:115]
	v_pk_mul_f32 v[28:29], v[28:29], v[102:103]
	v_pk_mul_f32 v[24:25], v[24:25], v[106:107]
	v_pk_mul_f32 v[20:21], v[20:21], v[110:111]
	v_pk_mul_f32 v[30:31], v[30:31], v[104:105]
	v_pk_mul_f32 v[26:27], v[26:27], v[108:109]
	v_pk_mul_f32 v[22:23], v[22:23], v[112:113]
	v_pk_mul_f32 v[18:19], v[18:19], v[116:117]
	v_pk_mul_f32 v[16:17], v[16:17], v[114:115]
.LBB0_974:
	v_cndmask_b32_e64 v97, v97, v168, s[8:9]
	v_mul_f32_e32 v97, 0xbe0293ee, v97
	v_fmamk_f32 v80, v80, 0x3e0293ee, v97
	v_fmamk_f32 v81, v81, 0x3e0293ee, v97
	v_fmamk_f32 v98, v82, 0x3e0293ee, v97
	v_exp_f32_e32 v82, v80
	v_fmamk_f32 v99, v84, 0x3e0293ee, v97
	v_exp_f32_e32 v84, v81
	v_fmamk_f32 v83, v83, 0x3e0293ee, v97
	v_exp_f32_e32 v80, v98
	v_fmamk_f32 v64, v64, 0x3e0293ee, v97
	v_exp_f32_e32 v83, v83
	v_fmamk_f32 v102, v85, 0x3e0293ee, v97
	v_fmamk_f32 v111, v94, 0x3e0293ee, v97
	v_fmamk_f32 v94, v75, 0x3e0293ee, v97
	v_exp_f32_e32 v75, v99
	v_exp_f32_e32 v98, v64
	v_add_f32_e32 v64, 0, v82
	v_fmamk_f32 v103, v86, 0x3e0293ee, v97
	v_exp_f32_e32 v81, v102
	v_add_f32_e32 v64, v84, v64
	v_fmamk_f32 v104, v87, 0x3e0293ee, v97
	v_fmamk_f32 v110, v93, 0x3e0293ee, v97
	v_fmamk_f32 v93, v74, 0x3e0293ee, v97
	v_exp_f32_e32 v74, v103
	v_add_f32_e32 v64, v80, v64
	v_fmamk_f32 v105, v88, 0x3e0293ee, v97
	v_fmamk_f32 v112, v95, 0x3e0293ee, v97
	v_fmamk_f32 v95, v76, 0x3e0293ee, v97
	v_exp_f32_e32 v76, v104
	v_add_f32_e32 v64, v83, v64
	v_fmamk_f32 v106, v89, 0x3e0293ee, v97
	v_fmamk_f32 v107, v90, 0x3e0293ee, v97
	v_fmamk_f32 v90, v71, 0x3e0293ee, v97
	v_exp_f32_e32 v71, v105
	v_add_f32_e32 v64, v75, v64
	v_fmamk_f32 v109, v92, 0x3e0293ee, v97
	v_fmamk_f32 v92, v73, 0x3e0293ee, v97
	v_exp_f32_e32 v73, v106
	v_add_f32_e32 v64, v81, v64
	v_fmamk_f32 v108, v91, 0x3e0293ee, v97
	v_fmamk_f32 v88, v69, 0x3e0293ee, v97
	v_exp_f32_e32 v69, v107
	v_add_f32_e32 v64, v74, v64
	v_fmamk_f32 v91, v72, 0x3e0293ee, v97
	v_exp_f32_e32 v72, v108
	v_add_f32_e32 v64, v76, v64
	v_fmamk_f32 v86, v67, 0x3e0293ee, v97
	v_exp_f32_e32 v67, v109
	v_add_f32_e32 v64, v71, v64
	v_fmamk_f32 v89, v70, 0x3e0293ee, v97
	v_exp_f32_e32 v70, v110
	v_add_f32_e32 v64, v73, v64
	v_fmamk_f32 v85, v66, 0x3e0293ee, v97
	v_exp_f32_e32 v66, v111
	v_add_f32_e32 v64, v69, v64
	v_fmamk_f32 v87, v68, 0x3e0293ee, v97
	v_exp_f32_e32 v68, v112
	v_add_f32_e32 v64, v72, v64
	v_fmamk_f32 v65, v65, 0x3e0293ee, v97
	v_add_f32_e32 v64, v67, v64
	v_exp_f32_e32 v99, v65
	v_add_f32_e32 v64, v70, v64
	v_exp_f32_e32 v85, v85
	v_add_f32_e32 v64, v66, v64
	v_exp_f32_e32 v86, v86
	v_add_f32_e32 v64, v68, v64
	v_exp_f32_e32 v87, v87
	v_add_f32_e32 v64, v98, v64
	v_exp_f32_e32 v88, v88
	v_add_f32_e32 v64, v99, v64
	v_exp_f32_e32 v89, v89
	v_add_f32_e32 v64, v85, v64
	v_exp_f32_e32 v90, v90
	v_add_f32_e32 v64, v86, v64
	v_exp_f32_e32 v91, v91
	v_add_f32_e32 v64, v87, v64
	v_exp_f32_e32 v92, v92
	v_add_f32_e32 v64, v88, v64
	v_exp_f32_e32 v93, v93
	v_add_f32_e32 v64, v89, v64
	v_exp_f32_e32 v94, v94
	v_add_f32_e32 v64, v90, v64
	v_fmamk_f32 v77, v77, 0x3e0293ee, v97
	v_exp_f32_e32 v95, v95
	v_add_f32_e32 v64, v91, v64
	v_fmamk_f32 v78, v78, 0x3e0293ee, v97
	v_exp_f32_e32 v102, v77
	v_add_f32_e32 v64, v92, v64
	v_fmac_f32_e32 v97, 0x3e0293ee, v79
	v_exp_f32_e32 v103, v78
	v_add_f32_e32 v64, v93, v64
	v_exp_f32_e32 v97, v97
	v_add_f32_e32 v64, v94, v64
	v_add_f32_e32 v64, v95, v64
	v_add_f32_e32 v64, v102, v64
	v_add_f32_e32 v64, v103, v64
	v_add_f32_e32 v64, v97, v64
	v_mov_b32_e32 v65, v64
	s_nop 1
	v_permlane32_swap_b32_e32 v64, v65
	v_cvt_pk_bf16_f32 v78, v82, v84
	v_cvt_pk_bf16_f32 v79, v80, v83
	v_cvt_pk_bf16_f32 v80, v75, v81
	v_cvt_pk_bf16_f32 v81, v74, v76
	v_cvt_pk_bf16_f32 v74, v71, v73
	v_cvt_pk_bf16_f32 v75, v69, v72
	v_cvt_pk_bf16_f32 v76, v67, v70
	v_cvt_pk_bf16_f32 v77, v66, v68
	v_cvt_pk_bf16_f32 v66, v98, v99
	v_cvt_pk_bf16_f32 v67, v85, v86
	v_cvt_pk_bf16_f32 v68, v87, v88
	v_cvt_pk_bf16_f32 v69, v89, v90
	v_cvt_pk_bf16_f32 v70, v91, v92
	v_cvt_pk_bf16_f32 v71, v93, v94
	v_cvt_pk_bf16_f32 v72, v95, v102
	v_cvt_pk_bf16_f32 v73, v103, v97
	s_nop 0
	v_permlane32_swap_b32_e32 v78, v80
	v_permlane32_swap_b32_e32 v79, v81
	v_permlane32_swap_b32_e32 v74, v76
	v_permlane32_swap_b32_e32 v75, v77
	v_permlane32_swap_b32_e32 v66, v68
	v_permlane32_swap_b32_e32 v67, v69
	v_permlane32_swap_b32_e32 v70, v72
	v_permlane32_swap_b32_e32 v71, v73
	ds_read_b64_tr_b16 v[82:83], v193 offset:0
	ds_read_b64_tr_b16 v[84:85], v193 offset:0x800
	ds_read_b64_tr_b16 v[86:87], v193 offset:0x1000
	ds_read_b64_tr_b16 v[88:89], v193 offset:0x1800
	ds_read_b64_tr_b16 v[90:91], v193 offset:0x2000
	ds_read_b64_tr_b16 v[92:93], v193 offset:0x2800
	ds_read_b64_tr_b16 v[102:103], v193 offset:0x3000
	ds_read_b64_tr_b16 v[104:105], v193 offset:0x3800
	s_nop 0
	s_waitcnt lgkmcnt(6)
	v_mfma_f32_32x32x16_bf16 v[0:15], v[78:81], v[82:85], v[0:15]
	ds_read_b64_tr_b16 v[82:83], v193 offset:0x200
	ds_read_b64_tr_b16 v[84:85], v193 offset:0xa00
	s_waitcnt lgkmcnt(6)
	v_mfma_f32_32x32x16_bf16 v[0:15], v[74:77], v[86:89], v[0:15]
	ds_read_b64_tr_b16 v[86:87], v193 offset:0x1200
	ds_read_b64_tr_b16 v[88:89], v193 offset:0x1a00
	s_waitcnt lgkmcnt(6)
	v_mfma_f32_32x32x16_bf16 v[0:15], v[66:69], v[90:93], v[0:15]
	ds_read_b64_tr_b16 v[90:91], v193 offset:0x2200
	ds_read_b64_tr_b16 v[92:93], v193 offset:0x2a00
	s_waitcnt lgkmcnt(6)
	v_mfma_f32_32x32x16_bf16 v[0:15], v[70:73], v[102:105], v[0:15]
	ds_read_b64_tr_b16 v[102:103], v193 offset:0x3200
	ds_read_b64_tr_b16 v[104:105], v193 offset:0x3a00
	s_waitcnt lgkmcnt(6)
	v_mfma_f32_32x32x16_bf16 v[48:63], v[78:81], v[82:85], v[48:63]
	ds_read_b64_tr_b16 v[82:83], v193 offset:0x400
	ds_read_b64_tr_b16 v[84:85], v193 offset:0xc00
	s_waitcnt lgkmcnt(6)
	v_mfma_f32_32x32x16_bf16 v[48:63], v[74:77], v[86:89], v[48:63]
	ds_read_b64_tr_b16 v[86:87], v193 offset:0x1400
	ds_read_b64_tr_b16 v[88:89], v193 offset:0x1c00
	s_waitcnt lgkmcnt(6)
	v_mfma_f32_32x32x16_bf16 v[48:63], v[66:69], v[90:93], v[48:63]
	ds_read_b64_tr_b16 v[90:91], v193 offset:0x2400
	ds_read_b64_tr_b16 v[92:93], v193 offset:0x2c00
	s_waitcnt lgkmcnt(6)
	v_mfma_f32_32x32x16_bf16 v[48:63], v[70:73], v[102:105], v[48:63]
	ds_read_b64_tr_b16 v[102:103], v193 offset:0x3400
	ds_read_b64_tr_b16 v[104:105], v193 offset:0x3c00
	s_waitcnt lgkmcnt(6)
	v_mfma_f32_32x32x16_bf16 v[32:47], v[78:81], v[82:85], v[32:47]
	ds_read_b64_tr_b16 v[82:83], v193 offset:0x600
	ds_read_b64_tr_b16 v[84:85], v193 offset:0xe00
	s_waitcnt lgkmcnt(6)
	v_mfma_f32_32x32x16_bf16 v[32:47], v[74:77], v[86:89], v[32:47]
	ds_read_b64_tr_b16 v[86:87], v193 offset:0x1600
	ds_read_b64_tr_b16 v[88:89], v193 offset:0x1e00
	s_waitcnt lgkmcnt(6)
	v_mfma_f32_32x32x16_bf16 v[32:47], v[66:69], v[90:93], v[32:47]
	ds_read_b64_tr_b16 v[90:91], v193 offset:0x2600
	ds_read_b64_tr_b16 v[92:93], v193 offset:0x2e00
	s_waitcnt lgkmcnt(6)
	v_mfma_f32_32x32x16_bf16 v[32:47], v[70:73], v[102:105], v[32:47]
	ds_read_b64_tr_b16 v[102:103], v193 offset:0x3600
	ds_read_b64_tr_b16 v[104:105], v193 offset:0x3e00
	s_waitcnt lgkmcnt(6)
	v_mfma_f32_32x32x16_bf16 v[16:31], v[78:81], v[82:85], v[16:31]
	s_waitcnt lgkmcnt(4)
	v_mfma_f32_32x32x16_bf16 v[16:31], v[74:77], v[86:89], v[16:31]
	s_waitcnt lgkmcnt(2)
	v_mfma_f32_32x32x16_bf16 v[16:31], v[66:69], v[90:93], v[16:31]
	s_waitcnt lgkmcnt(0)
	v_mfma_f32_32x32x16_bf16 v[16:31], v[70:73], v[102:105], v[16:31]
	s_and_saveexec_b64 s[8:9], s[6:7]
	s_cbranch_execz .LBB0_948
	v_add_f32_e32 v66, v100, v101
	v_fmac_f32_e32 v66, v192, v160
	v_add_f32_e32 v64, v64, v65
	v_fmac_f32_e32 v64, v66, v96
	ds_write_b32 v191, v64
	s_branch .LBB0_948
